# MLA HTSP: exp/cvt spread 2 per MFMA gap over QK and first PV round
# baseline (speedup 1.0000x reference)
.Lm_goA:
	s_setprio 1
	s_waitcnt lgkmcnt(13)
	v_mfma_f32_32x32x16_bf16 v[50:65], v[182:185], v[82:85], v[34:49]
	v_exp_f32_e32 v66, v66
	v_exp_f32_e32 v67, v67
	s_waitcnt lgkmcnt(12)
	v_mfma_f32_32x32x16_bf16 v[50:65], v[186:189], v[86:89], v[50:65]
	v_exp_f32_e32 v68, v68
	v_exp_f32_e32 v69, v69
	v_cvt_pk_bf16_f32 v152, v66, v67
	s_waitcnt lgkmcnt(11)
	v_mfma_f32_32x32x16_bf16 v[50:65], v[190:193], v[90:93], v[50:65]
	v_exp_f32_e32 v70, v70
	v_exp_f32_e32 v71, v71
	v_cvt_pk_bf16_f32 v153, v68, v69
	s_waitcnt lgkmcnt(10)
	v_mfma_f32_32x32x16_bf16 v[50:65], v[202:205], v[94:97], v[50:65]
	v_exp_f32_e32 v72, v72
	v_exp_f32_e32 v73, v73
	v_cvt_pk_bf16_f32 v154, v70, v71
	s_waitcnt lgkmcnt(9)
	v_mfma_f32_32x32x16_bf16 v[50:65], v[206:209], v[98:101], v[50:65]
	v_exp_f32_e32 v74, v74
	v_exp_f32_e32 v75, v75
	v_cvt_pk_bf16_f32 v155, v72, v73
	s_waitcnt lgkmcnt(8)
	v_mfma_f32_32x32x16_bf16 v[50:65], v[210:213], v[102:105], v[50:65]
	v_exp_f32_e32 v76, v76
	v_exp_f32_e32 v77, v77
	v_cvt_pk_bf16_f32 v214, v74, v75
	s_waitcnt lgkmcnt(6)
	v_mfma_f32_32x32x16_bf16 v[2:17], v[118:121], v[152:155], v[2:17]
	v_exp_f32_e32 v78, v78
	v_exp_f32_e32 v79, v79
	v_cvt_pk_bf16_f32 v215, v76, v77
	v_add_f32_e32 v218, v66, v68
	v_add_f32_e32 v219, v67, v69
	s_waitcnt lgkmcnt(4)
	v_mfma_f32_32x32x16_bf16 v[18:33], v[122:125], v[152:155], v[18:33]
	v_exp_f32_e32 v80, v80
	v_exp_f32_e32 v81, v81
	v_cvt_pk_bf16_f32 v216, v78, v79
	v_cvt_pk_bf16_f32 v217, v80, v81
	v_add_f32_e32 v218, v218, v70
	v_add_f32_e32 v219, v219, v71
	ds_read_b128 v[182:185], v239 offset:6656
	ds_read_b128 v[186:189], v239 offset:6688
	ds_read_b128 v[190:193], v239 offset:6720
	ds_read_b128 v[202:205], v239 offset:6752
	ds_read_b128 v[206:209], v239 offset:6784
	ds_read_b128 v[210:213], v239 offset:6816
	s_waitcnt lgkmcnt(8)
	v_mfma_f32_32x32x16_bf16 v[2:17], v[144:147], v[214:217], v[2:17]
	v_add_f32_e32 v218, v218, v72
	v_add_f32_e32 v219, v219, v73
	v_add_f32_e32 v218, v218, v74
	v_add_f32_e32 v219, v219, v75
	v_add_f32_e32 v218, v218, v76
	v_add_f32_e32 v219, v219, v77
	s_waitcnt lgkmcnt(6)
	v_mfma_f32_32x32x16_bf16 v[18:33], v[148:151], v[214:217], v[18:33]
	s_setprio 0
	v_max3_f32 v236, v50, v51, v52
	v_max3_f32 v237, v53, v54, v55
	v_max3_f32 v236, v236, v56, v57
	v_max3_f32 v237, v237, v58, v59
	v_max3_f32 v236, v236, v60, v61
	v_max3_f32 v237, v237, v62, v63
	v_max3_f32 v236, v236, v64, v65
	v_max_f32_e32 v236, v236, v237
	v_cmp_lt_f32_e64 s[100:101], s61, v236
	ds_read_b64_tr_b16 v[220:221], v240 offset:19456
	ds_read_b64_tr_b16 v[222:223], v240 offset:20992
	ds_read_b64_tr_b16 v[224:225], v240 offset:19520
	ds_read_b64_tr_b16 v[226:227], v240 offset:21056
	ds_read_b64_tr_b16 v[228:229], v240 offset:22528
	ds_read_b64_tr_b16 v[230:231], v240 offset:24064
	ds_read_b64_tr_b16 v[232:233], v240 offset:22592
	ds_read_b64_tr_b16 v[234:235], v240 offset:24128
	v_add_f32_e32 v218, v218, v78
	v_add_f32_e32 v219, v219, v79
	v_add_f32_e32 v218, v218, v80
	v_add_f32_e32 v219, v219, v81
	v_add_f32_e32 v218, v218, v219
	v_add_f32_e32 v142, v142, v218
	s_cmp_lg_u64 s[100:101], 0
	s_cbranch_scc1 .Lm_rareB
.Lm_goB:
	s_setprio 1
	s_waitcnt lgkmcnt(13)
	v_mfma_f32_32x32x16_bf16 v[66:81], v[182:185], v[82:85], v[34:49]
	v_exp_f32_e32 v50, v50
	v_exp_f32_e32 v51, v51
	s_waitcnt lgkmcnt(12)
	v_mfma_f32_32x32x16_bf16 v[66:81], v[186:189], v[86:89], v[66:81]
	v_exp_f32_e32 v52, v52
	v_exp_f32_e32 v53, v53
	v_cvt_pk_bf16_f32 v152, v50, v51
	s_waitcnt lgkmcnt(11)
	v_mfma_f32_32x32x16_bf16 v[66:81], v[190:193], v[90:93], v[66:81]
	v_exp_f32_e32 v54, v54
	v_exp_f32_e32 v55, v55
	v_cvt_pk_bf16_f32 v153, v52, v53
	s_waitcnt lgkmcnt(10)
	v_mfma_f32_32x32x16_bf16 v[66:81], v[202:205], v[94:97], v[66:81]
	v_exp_f32_e32 v56, v56
	v_exp_f32_e32 v57, v57
	v_cvt_pk_bf16_f32 v154, v54, v55
	s_waitcnt lgkmcnt(9)
	v_mfma_f32_32x32x16_bf16 v[66:81], v[206:209], v[98:101], v[66:81]
	v_exp_f32_e32 v58, v58
	v_exp_f32_e32 v59, v59
	v_cvt_pk_bf16_f32 v155, v56, v57
	s_waitcnt lgkmcnt(8)
	v_mfma_f32_32x32x16_bf16 v[66:81], v[210:213], v[102:105], v[66:81]
	v_exp_f32_e32 v60, v60
	v_exp_f32_e32 v61, v61
	v_cvt_pk_bf16_f32 v214, v58, v59
	s_waitcnt lgkmcnt(6)
	v_mfma_f32_32x32x16_bf16 v[2:17], v[220:223], v[152:155], v[2:17]
	v_exp_f32_e32 v62, v62
	v_exp_f32_e32 v63, v63
	v_cvt_pk_bf16_f32 v215, v60, v61
	v_add_f32_e32 v218, v50, v52
	v_add_f32_e32 v219, v51, v53
	s_waitcnt lgkmcnt(4)
	v_mfma_f32_32x32x16_bf16 v[18:33], v[224:227], v[152:155], v[18:33]
	v_exp_f32_e32 v64, v64
	v_exp_f32_e32 v65, v65
	v_cvt_pk_bf16_f32 v216, v62, v63
	v_cvt_pk_bf16_f32 v217, v64, v65
	v_add_f32_e32 v218, v218, v54
	v_add_f32_e32 v219, v219, v55
	s_waitcnt lgkmcnt(2)
	v_mfma_f32_32x32x16_bf16 v[2:17], v[228:231], v[214:217], v[2:17]
	v_add_f32_e32 v218, v218, v56
	v_add_f32_e32 v219, v219, v57
	v_add_f32_e32 v218, v218, v58
	v_add_f32_e32 v219, v219, v59
	v_add_f32_e32 v218, v218, v60
	v_add_f32_e32 v219, v219, v61
	s_waitcnt lgkmcnt(0)
	v_mfma_f32_32x32x16_bf16 v[18:33], v[232:235], v[214:217], v[18:33]
	s_setprio 0
	v_max3_f32 v236, v66, v67, v68
	v_max3_f32 v237, v69, v70, v71
	v_max3_f32 v236, v236, v72, v73
	v_max3_f32 v237, v237, v74, v75
	v_max3_f32 v236, v236, v76, v77
	v_max3_f32 v237, v237, v78, v79
	v_max3_f32 v236, v236, v80, v81
	v_max_f32_e32 v236, v236, v237
	v_cmp_lt_f32_e64 s[100:101], s61, v236
	v_add_f32_e32 v218, v218, v62
	v_add_f32_e32 v219, v219, v63
	v_add_f32_e32 v218, v218, v64
	v_add_f32_e32 v219, v219, v65
	v_add_f32_e32 v218, v218, v219
	v_add_f32_e32 v142, v142, v218
	s_cmp_eq_u32 s0, 0xfc0000
	s_cbranch_scc1 .Lm_next
	s_xor_b32 s4, s11, 1
	s_mulk_i32 s4, 0x6400
	s_mov_b32 s6, s4
	v_add3_u32 v241, s6, v134, v133
	s_waitcnt vmcnt(1)
	ds_write_b128 v241, v[110:113]
	s_and_saveexec_b64 s[4:5], s[2:3]
	v_add3_u32 v241, s6, v135, v136
	ds_write_b128 v241, v[106:109] offset:128
	s_or_b64 exec, exec, s[4:5]
	v_add3_u32 v241, s6, v137, v133
	s_cmp_gt_u32 s10, 61
	s_waitcnt vmcnt(0)
	ds_write_b128 v241, v[114:117] offset:13312
	s_cbranch_scc1 .Lm_next
	v_lshl_add_u64 v[242:243], v[130:131], 0, s[0:1]
	v_add_co_u32_e32 v110, vcc, 0x150a0000, v242
	s_nop 1
	v_addc_co_u32_e32 v111, vcc, 0, v243, vcc
	global_load_dwordx4 v[110:113], v[110:111], off
	s_and_saveexec_b64 s[4:5], s[2:3]
	s_cbranch_execz .Lm_nok2
	global_load_dwordx4 v[106:109], v[128:129], off
